# v14 + V tile 0 requested at the start of the softmax (into a free register set), first PV trip stages LDS from it
# speedup vs baseline: 1.0505x; 1.0012x over previous
.LBB0_785:
	s_waitcnt vmcnt(5)
	v_add_u32_e32 v11, v56, v194
	s_waitcnt lgkmcnt(0)
	ds_read_b128 v[0:3], v11
	ds_read_b128 v[4:7], v11 offset:1024
	v_lshlrev_b64 v[32:33], 1, v[52:53]
	v_lshl_add_u64 v[66:67], s[58:59], 0, v[32:33]
	v_lshl_add_u64 v[68:69], s[56:57], 0, v[32:33]
	s_waitcnt lgkmcnt(1)
	v_max_f32_e32 v8, v3, v3
	v_max_f32_e32 v9, v2, v2
	v_max_f32_e32 v8, v9, v8
	v_max3_f32 v8, v0, v1, v8
	v_add3_u32 v32, v56, v209, v208
	v_add3_u32 v33, v56, v211, v210
	v_mov_b32_dpp v9, v8 quad_perm:[1,0,3,2] row_mask:0xf bank_mask:0xf bound_ctrl:1
	v_max_f32_e32 v9, v9, v9
	v_max_f32_e32 v8, v8, v9
	v_add3_u32 v34, v56, v212, v208
	v_add3_u32 v35, v56, v213, v210
	v_mov_b32_dpp v9, v8 quad_perm:[2,3,0,1] row_mask:0xf bank_mask:0xf bound_ctrl:1
	v_max_f32_e32 v9, v9, v9
	v_max_f32_e32 v8, v8, v9
	s_waitcnt vmcnt(0)
	ds_read_u16 v240, v72
	ds_read_u16 v241, v72 offset:8
	ds_read_u16 v242, v72 offset:16
	ds_read_u16 v243, v72 offset:24
	ds_read_u16 v244, v72 offset:32
	ds_read_u16 v245, v72 offset:40
	ds_read_u16 v246, v72 offset:48
	ds_read_u16 v247, v72 offset:56
	s_waitcnt lgkmcnt(0)
	v_lshl_add_u32 v240, v240, 9, v64
	v_lshl_add_u32 v241, v241, 9, v64
	v_lshl_add_u32 v242, v242, 9, v64
	v_lshl_add_u32 v243, v243, 9, v64
	v_lshl_add_u32 v244, v244, 9, v64
	v_lshl_add_u32 v245, v245, 9, v64
	v_lshl_add_u32 v246, v246, 9, v64
	v_lshl_add_u32 v247, v247, 9, v64
	global_load_dwordx4 v[96:99], v240, s[54:55]
	global_load_dwordx4 v[100:103], v241, s[54:55]
	global_load_dwordx4 v[104:107], v242, s[54:55]
	global_load_dwordx4 v[108:111], v243, s[54:55]
	global_load_dwordx4 v[112:115], v244, s[54:55]
	global_load_dwordx4 v[116:119], v245, s[54:55]
	global_load_dwordx4 v[120:123], v246, s[54:55]
	global_load_dwordx4 v[124:127], v247, s[54:55]
	v_add3_u32 v36, v56, v214, v208
	v_add3_u32 v37, v56, v215, v210
	v_mov_b32_dpp v9, v8 row_half_mirror row_mask:0xf bank_mask:0xf bound_ctrl:1
	v_max_f32_e32 v9, v9, v9
	v_max_f32_e32 v8, v8, v9
	v_add3_u32 v38, v56, v216, v208
	v_add3_u32 v39, v56, v217, v210
	v_mov_b32_dpp v9, v8 row_mirror row_mask:0xf bank_mask:0xf bound_ctrl:1
	v_max_f32_e32 v9, v9, v9
	v_max_f32_e32 v8, v8, v9
	v_add3_u32 v40, v56, v218, v208
	v_readlane_b32 s2, v8, 32
	v_readlane_b32 s20, v8, 48
	v_readlane_b32 s0, v8, 0
	v_readlane_b32 s1, v8, 16
	v_max_f32_e64 v8, s20, s20
	v_max_f32_e64 v9, s2, s2
	v_max_f32_e32 v8, v9, v8
	v_mov_b32_e32 v9, s1
	v_max3_f32 v8, s0, v9, v8
	v_sub_f32_e32 v0, v0, v8
	v_sub_f32_e32 v1, v1, v8
	v_mul_f32_e32 v0, 0x3fb8aa3b, v0
	v_mul_f32_e32 v1, 0x3fb8aa3b, v1
	v_sub_f32_e32 v2, v2, v8
	v_exp_f32_e32 v0, v0
	v_exp_f32_e32 v1, v1
	v_mul_f32_e32 v2, 0x3fb8aa3b, v2
	v_sub_f32_e32 v3, v3, v8
	v_exp_f32_e32 v2, v2
	v_mul_f32_e32 v3, 0x3fb8aa3b, v3
	v_exp_f32_e32 v3, v3
	v_add_f32_e32 v8, v0, v1
	v_add_f32_e32 v8, v2, v8
	v_add3_u32 v41, v56, v219, v210
	v_add_f32_e32 v8, v3, v8
	v_add3_u32 v42, v56, v220, v208
	v_add3_u32 v43, v56, v221, v210
	v_add_f32_dpp v8, v8, v8 quad_perm:[1,0,3,2] row_mask:0xf bank_mask:0xf bound_ctrl:1
	v_add3_u32 v44, v56, v222, v208
	v_add3_u32 v45, v56, v223, v210
	v_add_f32_dpp v8, v8, v8 quad_perm:[2,3,0,1] row_mask:0xf bank_mask:0xf bound_ctrl:1
	v_add3_u32 v46, v56, v224, v208
	v_add3_u32 v47, v56, v225, v210
	v_add_f32_dpp v8, v8, v8 row_half_mirror row_mask:0xf bank_mask:0xf bound_ctrl:1
	v_add3_u32 v77, v56, v207, v148
	v_add_u32_e32 v78, v32, v206
	v_add_f32_dpp v8, v8, v8 row_mirror row_mask:0xf bank_mask:0xf bound_ctrl:1
	v_add_u32_e32 v79, v33, v206
	v_readlane_b32 s1, v8, 16
	v_readlane_b32 s20, v8, 48
	v_readlane_b32 s0, v8, 0
	v_readlane_b32 s2, v8, 32
	v_mov_b32_e32 v8, s1
	v_mov_b32_e32 v9, s20
	v_add_f32_e32 v8, s0, v8
	v_add_f32_e32 v9, s2, v9
	v_add_f32_e32 v8, v8, v9
	v_add_u32_e32 v80, v34, v206
	v_add_u32_e32 v81, v35, v206
	v_add_u32_e32 v82, v36, v206
	v_rcp_f32_e32 v8, v8
	s_nop 0
	v_mul_f32_e32 v0, v0, v8
	v_mul_f32_e32 v1, v1, v8
	v_bfe_u32 v9, v0, 16, 1
	v_add3_u32 v0, v0, v9, s79
	v_bfe_u32 v9, v1, 16, 1
	v_lshrrev_b32_e32 v0, 16, v0
	v_add3_u32 v1, v1, v9, s79
	v_and_or_b32 v0, v1, s80, v0
	v_mul_f32_e32 v1, v2, v8
	v_mul_f32_e32 v2, v3, v8
	v_bfe_u32 v3, v1, 16, 1
	v_add3_u32 v1, v1, v3, s79
	s_waitcnt lgkmcnt(0)
	v_max_f32_e32 v3, v7, v7
	v_max_f32_e32 v8, v6, v6
	v_max_f32_e32 v3, v8, v3
	v_max3_f32 v3, v4, v5, v3
	v_bfe_u32 v10, v2, 16, 1
	v_lshrrev_b32_e32 v1, 16, v1
	v_mov_b32_dpp v8, v3 quad_perm:[1,0,3,2] row_mask:0xf bank_mask:0xf bound_ctrl:1
	v_max_f32_e32 v8, v8, v8
	v_max_f32_e32 v3, v3, v8
	v_add3_u32 v2, v2, v10, s79
	v_and_or_b32 v1, v2, s80, v1
	v_mov_b32_dpp v8, v3 quad_perm:[2,3,0,1] row_mask:0xf bank_mask:0xf bound_ctrl:1
	v_max_f32_e32 v8, v8, v8
	v_max_f32_e32 v3, v3, v8
	v_add_u32_e32 v83, v37, v206
	v_add_u32_e32 v84, v38, v206
	v_mov_b32_dpp v8, v3 row_half_mirror row_mask:0xf bank_mask:0xf bound_ctrl:1
	v_max_f32_e32 v8, v8, v8
	v_max_f32_e32 v3, v3, v8
	v_add_u32_e32 v85, v39, v206
	v_add_u32_e32 v86, v40, v206
	v_mov_b32_dpp v8, v3 row_mirror row_mask:0xf bank_mask:0xf bound_ctrl:1
	v_max_f32_e32 v8, v8, v8
	v_max_f32_e32 v3, v3, v8
	v_add_u32_e32 v87, v41, v206
	v_readlane_b32 s2, v3, 32
	v_readlane_b32 s20, v3, 48
	v_readlane_b32 s0, v3, 0
	v_readlane_b32 s1, v3, 16
	v_max_f32_e64 v3, s20, s20
	v_max_f32_e64 v8, s2, s2
	v_max_f32_e32 v3, v8, v3
	v_mov_b32_e32 v8, s1
	v_max3_f32 v3, s0, v8, v3
	v_sub_f32_e32 v4, v4, v3
	v_sub_f32_e32 v5, v5, v3
	v_mul_f32_e32 v4, 0x3fb8aa3b, v4
	v_mul_f32_e32 v5, 0x3fb8aa3b, v5
	v_sub_f32_e32 v6, v6, v3
	v_exp_f32_e32 v4, v4
	v_exp_f32_e32 v5, v5
	v_mul_f32_e32 v6, 0x3fb8aa3b, v6
	v_sub_f32_e32 v3, v7, v3
	v_exp_f32_e32 v6, v6
	v_mul_f32_e32 v3, 0x3fb8aa3b, v3
	v_exp_f32_e32 v3, v3
	v_add_f32_e32 v7, v4, v5
	v_add_f32_e32 v7, v6, v7
	v_add_u32_e32 v88, v42, v206
	v_add_f32_e32 v7, v3, v7
	v_add_u32_e32 v89, v43, v206
	v_add_u32_e32 v90, v44, v206
	v_add_f32_dpp v7, v7, v7 quad_perm:[1,0,3,2] row_mask:0xf bank_mask:0xf bound_ctrl:1
	v_add_u32_e32 v91, v45, v206
	v_add_u32_e32 v92, v46, v206
	v_add_f32_dpp v7, v7, v7 quad_perm:[2,3,0,1] row_mask:0xf bank_mask:0xf bound_ctrl:1
	v_add_u32_e32 v93, v47, v206
	s_nop 0
	v_add_f32_dpp v7, v7, v7 row_half_mirror row_mask:0xf bank_mask:0xf bound_ctrl:1
	s_nop 1
	v_add_f32_dpp v7, v7, v7 row_mirror row_mask:0xf bank_mask:0xf bound_ctrl:1
	s_nop 0
	v_readlane_b32 s1, v7, 16
	v_readlane_b32 s20, v7, 48
	v_readlane_b32 s0, v7, 0
	v_readlane_b32 s2, v7, 32
	v_mov_b32_e32 v7, s1
	v_mov_b32_e32 v8, s20
	v_add_f32_e32 v7, s0, v7
	v_add_f32_e32 v8, s2, v8
	v_add_f32_e32 v7, v7, v8
	s_nop 0
	v_rcp_f32_e32 v8, v7
	s_nop 0
	v_mul_f32_e32 v2, v4, v8
	v_mul_f32_e32 v4, v5, v8
	v_bfe_u32 v5, v2, 16, 1
	v_add3_u32 v2, v2, v5, s79
	v_bfe_u32 v5, v4, 16, 1
	v_lshrrev_b32_e32 v2, 16, v2
	v_add3_u32 v4, v4, v5, s79
	v_and_or_b32 v2, v4, s80, v2
	v_mul_f32_e32 v9, v6, v8
	ds_read_b128 v[4:7], v11 offset:2048
	v_mul_f32_e32 v3, v3, v8
	v_bfe_u32 v8, v9, 16, 1
	v_add3_u32 v8, v9, v8, s79
	v_bfe_u32 v17, v3, 16, 1
	s_waitcnt lgkmcnt(0)
	v_max_f32_e32 v9, v7, v7
	v_max_f32_e32 v10, v6, v6
	v_max_f32_e32 v9, v10, v9
	v_max3_f32 v9, v4, v5, v9
	v_lshrrev_b32_e32 v8, 16, v8
	v_add3_u32 v3, v3, v17, s79
	v_mov_b32_dpp v10, v9 quad_perm:[1,0,3,2] row_mask:0xf bank_mask:0xf bound_ctrl:1
	v_max_f32_e32 v10, v10, v10
	v_max_f32_e32 v9, v9, v10
	v_and_or_b32 v3, v3, s80, v8
	ds_read_b128 v[12:15], v11 offset:3072
	v_mov_b32_dpp v10, v9 quad_perm:[2,3,0,1] row_mask:0xf bank_mask:0xf bound_ctrl:1
	v_max_f32_e32 v10, v10, v10
	v_max_f32_e32 v9, v9, v10
	s_nop 1
	v_mov_b32_dpp v10, v9 row_half_mirror row_mask:0xf bank_mask:0xf bound_ctrl:1
	v_max_f32_e32 v10, v10, v10
	v_max_f32_e32 v9, v9, v10
	s_nop 1
	v_mov_b32_dpp v10, v9 row_mirror row_mask:0xf bank_mask:0xf bound_ctrl:1
	v_max_f32_e32 v10, v10, v10
	v_max_f32_e32 v9, v9, v10
	s_nop 0
	v_readlane_b32 s2, v9, 32
	v_readlane_b32 s20, v9, 48
	v_readlane_b32 s0, v9, 0
	v_readlane_b32 s1, v9, 16
	v_max_f32_e64 v9, s20, s20
	v_max_f32_e64 v10, s2, s2
	v_max_f32_e32 v9, v10, v9
	v_mov_b32_e32 v10, s1
	v_max3_f32 v9, s0, v10, v9
	v_sub_f32_e32 v4, v4, v9
	v_sub_f32_e32 v5, v5, v9
	v_mul_f32_e32 v4, 0x3fb8aa3b, v4
	v_mul_f32_e32 v5, 0x3fb8aa3b, v5
	v_sub_f32_e32 v6, v6, v9
	v_exp_f32_e32 v4, v4
	v_exp_f32_e32 v5, v5
	v_mul_f32_e32 v6, 0x3fb8aa3b, v6
	v_sub_f32_e32 v7, v7, v9
	v_exp_f32_e32 v6, v6
	v_mul_f32_e32 v7, 0x3fb8aa3b, v7
	v_exp_f32_e32 v7, v7
	v_add_f32_e32 v9, v4, v5
	v_add_f32_e32 v9, v6, v9
	v_add_f32_e32 v9, v7, v9
	s_nop 1
	v_add_f32_dpp v9, v9, v9 quad_perm:[1,0,3,2] row_mask:0xf bank_mask:0xf bound_ctrl:1
	s_nop 1
	v_add_f32_dpp v9, v9, v9 quad_perm:[2,3,0,1] row_mask:0xf bank_mask:0xf bound_ctrl:1
	s_nop 1
	v_add_f32_dpp v9, v9, v9 row_half_mirror row_mask:0xf bank_mask:0xf bound_ctrl:1
	s_nop 1
	v_add_f32_dpp v9, v9, v9 row_mirror row_mask:0xf bank_mask:0xf bound_ctrl:1
	s_nop 0
	v_readlane_b32 s1, v9, 16
	v_readlane_b32 s20, v9, 48
	v_readlane_b32 s0, v9, 0
	v_readlane_b32 s2, v9, 32
	v_mov_b32_e32 v9, s1
	v_mov_b32_e32 v10, s20
	v_add_f32_e32 v9, s0, v9
	v_add_f32_e32 v10, s2, v10
	v_add_f32_e32 v9, v9, v10
	s_nop 0
	v_rcp_f32_e32 v8, v9
	s_nop 0
	v_mul_f32_e32 v4, v4, v8
	v_mul_f32_e32 v5, v5, v8
	v_bfe_u32 v9, v4, 16, 1
	v_add3_u32 v4, v4, v9, s79
	v_bfe_u32 v9, v5, 16, 1
	v_lshrrev_b32_e32 v4, 16, v4
	v_add3_u32 v5, v5, v9, s79
	v_and_or_b32 v4, v5, s80, v4
	v_mul_f32_e32 v5, v6, v8
	v_mul_f32_e32 v6, v7, v8
	v_bfe_u32 v7, v5, 16, 1
	v_add3_u32 v5, v5, v7, s79
	s_waitcnt lgkmcnt(0)
	v_max_f32_e32 v7, v15, v15
	v_max_f32_e32 v8, v14, v14
	v_max_f32_e32 v7, v8, v7
	v_max3_f32 v7, v12, v13, v7
	v_lshrrev_b32_e32 v5, 16, v5
	s_nop 0
	v_mov_b32_dpp v8, v7 quad_perm:[1,0,3,2] row_mask:0xf bank_mask:0xf bound_ctrl:1
	v_max_f32_e32 v8, v8, v8
	v_max_f32_e32 v7, v7, v8
	s_nop 1
	v_mov_b32_dpp v8, v7 quad_perm:[2,3,0,1] row_mask:0xf bank_mask:0xf bound_ctrl:1
	v_max_f32_e32 v8, v8, v8
	v_max_f32_e32 v7, v7, v8
	s_nop 1
	v_mov_b32_dpp v8, v7 row_half_mirror row_mask:0xf bank_mask:0xf bound_ctrl:1
	v_max_f32_e32 v8, v8, v8
	v_max_f32_e32 v7, v7, v8
	s_nop 1
	v_mov_b32_dpp v8, v7 row_mirror row_mask:0xf bank_mask:0xf bound_ctrl:1
	v_max_f32_e32 v8, v8, v8
	v_max_f32_e32 v7, v7, v8
	s_nop 0
	v_readlane_b32 s2, v7, 32
	v_readlane_b32 s20, v7, 48
	v_readlane_b32 s0, v7, 0
	v_readlane_b32 s1, v7, 16
	v_max_f32_e64 v7, s20, s20
	v_max_f32_e64 v8, s2, s2
	v_max_f32_e32 v7, v8, v7
	v_mov_b32_e32 v8, s1
	v_max3_f32 v7, s0, v8, v7
	v_sub_f32_e32 v8, v12, v7
	v_sub_f32_e32 v9, v13, v7
	v_mul_f32_e32 v8, 0x3fb8aa3b, v8
	v_mul_f32_e32 v9, 0x3fb8aa3b, v9
	v_sub_f32_e32 v10, v14, v7
	v_exp_f32_e32 v8, v8
	v_exp_f32_e32 v9, v9
	v_mul_f32_e32 v10, 0x3fb8aa3b, v10
	v_sub_f32_e32 v7, v15, v7
	v_exp_f32_e32 v10, v10
	v_mul_f32_e32 v7, 0x3fb8aa3b, v7
	v_exp_f32_e32 v7, v7
	v_add_f32_e32 v12, v8, v9
	v_add_f32_e32 v12, v10, v12
	v_bfe_u32 v15, v6, 16, 1
	v_add_f32_e32 v12, v7, v12
	v_add3_u32 v6, v6, v15, s79
	v_and_or_b32 v5, v6, s80, v5
	v_add_f32_dpp v12, v12, v12 quad_perm:[1,0,3,2] row_mask:0xf bank_mask:0xf bound_ctrl:1
	s_nop 1
	v_add_f32_dpp v12, v12, v12 quad_perm:[2,3,0,1] row_mask:0xf bank_mask:0xf bound_ctrl:1
	s_nop 1
	v_add_f32_dpp v12, v12, v12 row_half_mirror row_mask:0xf bank_mask:0xf bound_ctrl:1
	s_nop 1
	v_add_f32_dpp v12, v12, v12 row_mirror row_mask:0xf bank_mask:0xf bound_ctrl:1
	s_nop 0
	v_readlane_b32 s1, v12, 16
	v_readlane_b32 s20, v12, 48
	v_readlane_b32 s0, v12, 0
	v_readlane_b32 s2, v12, 32
	v_mov_b32_e32 v12, s1
	v_mov_b32_e32 v13, s20
	v_add_f32_e32 v12, s0, v12
	v_add_f32_e32 v13, s2, v13
	v_add_f32_e32 v12, v12, v13
	s_nop 0
	v_rcp_f32_e32 v16, v12
	s_nop 0
	v_mul_f32_e32 v6, v8, v16
	v_mul_f32_e32 v8, v9, v16
	v_bfe_u32 v9, v6, 16, 1
	ds_read_b128 v[12:15], v11 offset:4096
	v_add3_u32 v6, v6, v9, s79
	v_bfe_u32 v9, v8, 16, 1
	v_lshrrev_b32_e32 v6, 16, v6
	v_add3_u32 v8, v8, v9, s79
	v_and_or_b32 v6, v8, s80, v6
	v_mul_f32_e32 v8, v10, v16
	v_bfe_u32 v9, v8, 16, 1
	v_add3_u32 v8, v8, v9, s79
	s_waitcnt lgkmcnt(0)
	v_max_f32_e32 v9, v15, v15
	v_max_f32_e32 v10, v14, v14
	v_max_f32_e32 v9, v10, v9
	v_max3_f32 v9, v12, v13, v9
	v_mul_f32_e32 v7, v7, v16
	v_bfe_u32 v21, v7, 16, 1
	v_mov_b32_dpp v10, v9 quad_perm:[1,0,3,2] row_mask:0xf bank_mask:0xf bound_ctrl:1
	v_max_f32_e32 v10, v10, v10
	v_max_f32_e32 v9, v9, v10
	v_lshrrev_b32_e32 v8, 16, v8
	v_add3_u32 v7, v7, v21, s79
	v_mov_b32_dpp v10, v9 quad_perm:[2,3,0,1] row_mask:0xf bank_mask:0xf bound_ctrl:1
	v_max_f32_e32 v10, v10, v10
	v_max_f32_e32 v9, v9, v10
	v_and_or_b32 v7, v7, s80, v8
	ds_read_b128 v[16:19], v11 offset:5120
	v_mov_b32_dpp v10, v9 row_half_mirror row_mask:0xf bank_mask:0xf bound_ctrl:1
	v_max_f32_e32 v10, v10, v10
	v_max_f32_e32 v9, v9, v10
	s_nop 1
	v_mov_b32_dpp v10, v9 row_mirror row_mask:0xf bank_mask:0xf bound_ctrl:1
	v_max_f32_e32 v10, v10, v10
	v_max_f32_e32 v9, v9, v10
	s_nop 0
	v_readlane_b32 s2, v9, 32
	v_readlane_b32 s20, v9, 48
	v_readlane_b32 s0, v9, 0
	v_readlane_b32 s1, v9, 16
	v_max_f32_e64 v9, s20, s20
	v_max_f32_e64 v10, s2, s2
	v_max_f32_e32 v9, v10, v9
	v_mov_b32_e32 v10, s1
	v_max3_f32 v9, s0, v10, v9
	v_sub_f32_e32 v10, v12, v9
	v_sub_f32_e32 v12, v13, v9
	v_mul_f32_e32 v10, 0x3fb8aa3b, v10
	v_mul_f32_e32 v12, 0x3fb8aa3b, v12
	v_sub_f32_e32 v13, v14, v9
	v_exp_f32_e32 v10, v10
	v_exp_f32_e32 v12, v12
	v_mul_f32_e32 v13, 0x3fb8aa3b, v13
	v_sub_f32_e32 v9, v15, v9
	v_exp_f32_e32 v13, v13
	v_mul_f32_e32 v9, 0x3fb8aa3b, v9
	v_exp_f32_e32 v9, v9
	v_add_f32_e32 v14, v10, v12
	v_add_f32_e32 v14, v13, v14
	v_add_f32_e32 v14, v9, v14
	s_nop 1
	v_add_f32_dpp v14, v14, v14 quad_perm:[1,0,3,2] row_mask:0xf bank_mask:0xf bound_ctrl:1
	s_nop 1
	v_add_f32_dpp v14, v14, v14 quad_perm:[2,3,0,1] row_mask:0xf bank_mask:0xf bound_ctrl:1
	s_nop 1
	v_add_f32_dpp v14, v14, v14 row_half_mirror row_mask:0xf bank_mask:0xf bound_ctrl:1
	s_nop 1
	v_add_f32_dpp v14, v14, v14 row_mirror row_mask:0xf bank_mask:0xf bound_ctrl:1
	s_nop 0
	v_readlane_b32 s1, v14, 16
	v_readlane_b32 s20, v14, 48
	v_readlane_b32 s0, v14, 0
	v_readlane_b32 s2, v14, 32
	v_mov_b32_e32 v14, s1
	v_mov_b32_e32 v15, s20
	v_add_f32_e32 v14, s0, v14
	v_add_f32_e32 v15, s2, v15
	v_add_f32_e32 v14, v14, v15
	s_nop 0
	v_rcp_f32_e32 v14, v14
	s_nop 0
	v_mul_f32_e32 v8, v10, v14
	v_mul_f32_e32 v10, v12, v14
	v_bfe_u32 v12, v8, 16, 1
	v_add3_u32 v8, v8, v12, s79
	v_bfe_u32 v12, v10, 16, 1
	v_lshrrev_b32_e32 v8, 16, v8
	v_add3_u32 v10, v10, v12, s79
	v_and_or_b32 v8, v10, s80, v8
	v_mul_f32_e32 v10, v13, v14
	v_bfe_u32 v12, v10, 16, 1
	v_add3_u32 v10, v10, v12, s79
	s_waitcnt lgkmcnt(0)
	v_max_f32_e32 v12, v19, v19
	v_max_f32_e32 v13, v18, v18
	v_max_f32_e32 v12, v13, v12
	v_max3_f32 v12, v16, v17, v12
	v_mul_f32_e32 v9, v9, v14
	v_lshrrev_b32_e32 v10, 16, v10
	v_mov_b32_dpp v13, v12 quad_perm:[1,0,3,2] row_mask:0xf bank_mask:0xf bound_ctrl:1
	v_max_f32_e32 v13, v13, v13
	v_max_f32_e32 v12, v12, v13
	s_nop 1
	v_mov_b32_dpp v13, v12 quad_perm:[2,3,0,1] row_mask:0xf bank_mask:0xf bound_ctrl:1
	v_max_f32_e32 v13, v13, v13
	v_max_f32_e32 v12, v12, v13
	s_nop 1
	v_mov_b32_dpp v13, v12 row_half_mirror row_mask:0xf bank_mask:0xf bound_ctrl:1
	v_max_f32_e32 v13, v13, v13
	v_max_f32_e32 v12, v12, v13
	s_nop 1
	v_mov_b32_dpp v13, v12 row_mirror row_mask:0xf bank_mask:0xf bound_ctrl:1
	v_max_f32_e32 v13, v13, v13
	v_max_f32_e32 v12, v12, v13
	s_nop 0
	v_readlane_b32 s2, v12, 32
	v_readlane_b32 s20, v12, 48
	v_readlane_b32 s0, v12, 0
	v_readlane_b32 s1, v12, 16
	v_max_f32_e64 v12, s20, s20
	v_max_f32_e64 v13, s2, s2
	v_max_f32_e32 v12, v13, v12
	v_mov_b32_e32 v13, s1
	v_max3_f32 v12, s0, v13, v12
	v_sub_f32_e32 v13, v16, v12
	v_sub_f32_e32 v14, v17, v12
	v_mul_f32_e32 v13, 0x3fb8aa3b, v13
	v_mul_f32_e32 v14, 0x3fb8aa3b, v14
	v_sub_f32_e32 v15, v18, v12
	v_exp_f32_e32 v13, v13
	v_exp_f32_e32 v14, v14
	v_mul_f32_e32 v15, 0x3fb8aa3b, v15
	v_sub_f32_e32 v12, v19, v12
	v_exp_f32_e32 v15, v15
	v_mul_f32_e32 v12, 0x3fb8aa3b, v12
	v_exp_f32_e32 v16, v12
	v_add_f32_e32 v12, v13, v14
	v_add_f32_e32 v12, v15, v12
	v_bfe_u32 v19, v9, 16, 1
	v_add_f32_e32 v12, v16, v12
	v_add3_u32 v9, v9, v19, s79
	v_and_or_b32 v9, v9, s80, v10
	v_add_f32_dpp v12, v12, v12 quad_perm:[1,0,3,2] row_mask:0xf bank_mask:0xf bound_ctrl:1
	s_nop 1
	v_add_f32_dpp v12, v12, v12 quad_perm:[2,3,0,1] row_mask:0xf bank_mask:0xf bound_ctrl:1
	s_nop 1
	v_add_f32_dpp v12, v12, v12 row_half_mirror row_mask:0xf bank_mask:0xf bound_ctrl:1
	s_nop 1
	v_add_f32_dpp v12, v12, v12 row_mirror row_mask:0xf bank_mask:0xf bound_ctrl:1
	s_nop 0
	v_readlane_b32 s1, v12, 16
	v_readlane_b32 s20, v12, 48
	v_readlane_b32 s0, v12, 0
	v_readlane_b32 s2, v12, 32
	v_mov_b32_e32 v12, s1
	v_mov_b32_e32 v17, s20
	v_add_f32_e32 v12, s0, v12
	v_add_f32_e32 v17, s2, v17
	v_add_f32_e32 v12, v12, v17
	s_nop 0
	v_rcp_f32_e32 v17, v12
	s_nop 0
	v_mul_f32_e32 v10, v13, v17
	v_mul_f32_e32 v12, v14, v17
	v_bfe_u32 v13, v10, 16, 1
	v_add3_u32 v10, v10, v13, s79
	v_bfe_u32 v13, v12, 16, 1
	v_lshrrev_b32_e32 v10, 16, v10
	v_add3_u32 v12, v12, v13, s79
	v_and_or_b32 v10, v12, s80, v10
	v_mul_f32_e32 v18, v15, v17
	ds_read_b128 v[12:15], v11 offset:6144
	v_mul_f32_e32 v20, v16, v17
	v_bfe_u32 v16, v18, 16, 1
	v_add3_u32 v21, v18, v16, s79
	ds_read_b128 v[16:19], v11 offset:7168
	s_waitcnt lgkmcnt(1)
	v_max_f32_e32 v11, v15, v15
	v_max_f32_e32 v22, v14, v14
	v_max_f32_e32 v11, v22, v11
	v_max3_f32 v11, v12, v13, v11
	v_bfe_u32 v24, v20, 16, 1
	v_add3_u32 v20, v20, v24, s79
	v_mov_b32_dpp v22, v11 quad_perm:[1,0,3,2] row_mask:0xf bank_mask:0xf bound_ctrl:1
	v_max_f32_e32 v22, v22, v22
	v_max_f32_e32 v11, v11, v22
	s_waitcnt lgkmcnt(0)
	s_nop 1
	v_mov_b32_dpp v22, v11 quad_perm:[2,3,0,1] row_mask:0xf bank_mask:0xf bound_ctrl:1
	v_max_f32_e32 v22, v22, v22
	v_max_f32_e32 v11, v11, v22
	s_nop 1
	v_mov_b32_dpp v22, v11 row_half_mirror row_mask:0xf bank_mask:0xf bound_ctrl:1
	v_max_f32_e32 v22, v22, v22
	v_max_f32_e32 v11, v11, v22
	s_nop 1
	v_mov_b32_dpp v22, v11 row_mirror row_mask:0xf bank_mask:0xf bound_ctrl:1
	v_max_f32_e32 v22, v22, v22
	v_max_f32_e32 v11, v11, v22
	s_nop 0
	v_readlane_b32 s2, v11, 32
	v_readlane_b32 s20, v11, 48
	v_readlane_b32 s0, v11, 0
	v_readlane_b32 s1, v11, 16
	v_max_f32_e64 v11, s20, s20
	v_max_f32_e64 v22, s2, s2
	v_max_f32_e32 v11, v22, v11
	v_mov_b32_e32 v22, s1
	v_max3_f32 v11, s0, v22, v11
	v_sub_f32_e32 v12, v12, v11
	v_sub_f32_e32 v13, v13, v11
	v_mul_f32_e32 v12, 0x3fb8aa3b, v12
	v_mul_f32_e32 v13, 0x3fb8aa3b, v13
	v_sub_f32_e32 v14, v14, v11
	v_exp_f32_e32 v12, v12
	v_exp_f32_e32 v13, v13
	v_mul_f32_e32 v14, 0x3fb8aa3b, v14
	v_sub_f32_e32 v11, v15, v11
	v_exp_f32_e32 v14, v14
	v_mul_f32_e32 v11, 0x3fb8aa3b, v11
	v_exp_f32_e32 v15, v11
	v_lshrrev_b32_e32 v11, 16, v21
	v_add_f32_e32 v21, v12, v13
	v_add_f32_e32 v21, v14, v21
	v_add_f32_e32 v21, v15, v21
	v_and_or_b32 v11, v20, s80, v11
	s_nop 0
	v_add_f32_dpp v21, v21, v21 quad_perm:[1,0,3,2] row_mask:0xf bank_mask:0xf bound_ctrl:1
	s_nop 1
	v_add_f32_dpp v21, v21, v21 quad_perm:[2,3,0,1] row_mask:0xf bank_mask:0xf bound_ctrl:1
	s_nop 1
	v_add_f32_dpp v21, v21, v21 row_half_mirror row_mask:0xf bank_mask:0xf bound_ctrl:1
	s_nop 1
	v_add_f32_dpp v21, v21, v21 row_mirror row_mask:0xf bank_mask:0xf bound_ctrl:1
	s_nop 0
	v_readlane_b32 s1, v21, 16
	v_readlane_b32 s20, v21, 48
	v_readlane_b32 s0, v21, 0
	v_readlane_b32 s2, v21, 32
	v_mov_b32_e32 v21, s1
	v_mov_b32_e32 v22, s20
	v_add_f32_e32 v21, s0, v21
	v_add_f32_e32 v22, s2, v22
	v_add_f32_e32 v21, v21, v22
	s_nop 0
	v_rcp_f32_e32 v20, v21
	s_nop 0
	v_mul_f32_e32 v12, v12, v20
	v_mul_f32_e32 v13, v13, v20
	v_bfe_u32 v21, v12, 16, 1
	v_add3_u32 v12, v12, v21, s79
	v_bfe_u32 v21, v13, 16, 1
	v_lshrrev_b32_e32 v12, 16, v12
	v_add3_u32 v13, v13, v21, s79
	v_and_or_b32 v12, v13, s80, v12
	v_mul_f32_e32 v13, v14, v20
	v_mul_f32_e32 v14, v15, v20
	v_bfe_u32 v15, v13, 16, 1
	v_add3_u32 v13, v13, v15, s79
	s_waitcnt lgkmcnt(0)
	v_max_f32_e32 v15, v19, v19
	v_max_f32_e32 v20, v18, v18
	v_max_f32_e32 v15, v20, v15
	v_max3_f32 v15, v16, v17, v15
	v_bfe_u32 v22, v14, 16, 1
	v_lshrrev_b32_e32 v13, 16, v13
	v_mov_b32_dpp v20, v15 quad_perm:[1,0,3,2] row_mask:0xf bank_mask:0xf bound_ctrl:1
	v_max_f32_e32 v20, v20, v20
	v_max_f32_e32 v15, v15, v20
	v_add3_u32 v14, v14, v22, s79
	v_and_or_b32 v13, v14, s80, v13
	v_mov_b32_dpp v20, v15 quad_perm:[2,3,0,1] row_mask:0xf bank_mask:0xf bound_ctrl:1
	v_max_f32_e32 v20, v20, v20
	v_max_f32_e32 v15, v15, v20
	s_nop 1
	v_mov_b32_dpp v20, v15 row_half_mirror row_mask:0xf bank_mask:0xf bound_ctrl:1
	v_max_f32_e32 v20, v20, v20
	v_max_f32_e32 v15, v15, v20
	s_nop 1
	v_mov_b32_dpp v20, v15 row_mirror row_mask:0xf bank_mask:0xf bound_ctrl:1
	v_max_f32_e32 v20, v20, v20
	v_max_f32_e32 v15, v15, v20
	s_nop 0
	v_readlane_b32 s2, v15, 32
	v_readlane_b32 s20, v15, 48
	v_readlane_b32 s0, v15, 0
	v_readlane_b32 s1, v15, 16
	v_max_f32_e64 v15, s20, s20
	v_max_f32_e64 v20, s2, s2
	v_max_f32_e32 v15, v20, v15
	v_mov_b32_e32 v20, s1
	v_max3_f32 v15, s0, v20, v15
	v_sub_f32_e32 v16, v16, v15
	v_sub_f32_e32 v17, v17, v15
	v_mul_f32_e32 v16, 0x3fb8aa3b, v16
	v_mul_f32_e32 v17, 0x3fb8aa3b, v17
	v_sub_f32_e32 v18, v18, v15
	v_exp_f32_e32 v16, v16
	v_exp_f32_e32 v17, v17
	v_mul_f32_e32 v18, 0x3fb8aa3b, v18
	v_sub_f32_e32 v15, v19, v15
	v_exp_f32_e32 v18, v18
	v_mul_f32_e32 v15, 0x3fb8aa3b, v15
	v_exp_f32_e32 v15, v15
	v_add_f32_e32 v19, v16, v17
	v_add_f32_e32 v19, v18, v19
	v_add_f32_e32 v19, v15, v19
	s_nop 1
	v_add_f32_dpp v19, v19, v19 quad_perm:[1,0,3,2] row_mask:0xf bank_mask:0xf bound_ctrl:1
	s_nop 1
	v_add_f32_dpp v19, v19, v19 quad_perm:[2,3,0,1] row_mask:0xf bank_mask:0xf bound_ctrl:1
	s_nop 1
	v_add_f32_dpp v19, v19, v19 row_half_mirror row_mask:0xf bank_mask:0xf bound_ctrl:1
	s_nop 1
	v_add_f32_dpp v19, v19, v19 row_mirror row_mask:0xf bank_mask:0xf bound_ctrl:1
	s_nop 0
	v_readlane_b32 s1, v19, 16
	v_readlane_b32 s20, v19, 48
	v_readlane_b32 s0, v19, 0
	v_readlane_b32 s2, v19, 32
	v_mov_b32_e32 v19, s1
	v_mov_b32_e32 v20, s20
	v_add_f32_e32 v19, s0, v19
	v_add_f32_e32 v20, s2, v20
	v_add_f32_e32 v19, v19, v20
	s_mov_b32 s2, 0
	s_mov_b64 s[0:1], -1
	v_rcp_f32_e32 v19, v19
	s_nop 0
	v_mul_f32_e32 v14, v16, v19
	v_mul_f32_e32 v16, v17, v19
	v_bfe_u32 v17, v14, 16, 1
	v_add3_u32 v14, v14, v17, s79
	v_bfe_u32 v17, v16, 16, 1
	v_lshrrev_b32_e32 v14, 16, v14
	v_add3_u32 v16, v16, v17, s79
	v_and_or_b32 v14, v16, s80, v14
	v_mul_f32_e32 v16, v18, v19
	v_mul_f32_e32 v15, v15, v19
	v_bfe_u32 v17, v16, 16, 1
	v_add3_u32 v16, v16, v17, s79
	v_bfe_u32 v17, v15, 16, 1
	v_lshrrev_b32_e32 v16, 16, v16
	v_add3_u32 v15, v15, v17, s79
	v_and_or_b32 v15, v15, s80, v16
	v_add_u32_e32 v16, v56, v195
	ds_write2st64_b64 v16, v[0:1], v[2:3] offset1:1
	ds_write2st64_b64 v16, v[4:5], v[6:7] offset0:2 offset1:3
	ds_write2st64_b64 v16, v[8:9], v[10:11] offset0:4 offset1:5
	ds_write2st64_b64 v16, v[12:13], v[14:15] offset0:6 offset1:7
	s_waitcnt lgkmcnt(0)
	s_branch .LBB0_787

.LBB0_789:
	s_cmp_eq_u32 s20, 0
	s_cbranch_scc1 .Lpv_first
	s_cmp_gt_u32 s20, 14
	s_cbranch_scc1 .Lpv_last
	s_and_b32 s24, s22, 0xe0
	v_lshl_add_u32 v110, s24, 1, v72
	ds_read_u16 v111, v110
	ds_read_u16 v112, v110 offset:8
	ds_read_u16 v113, v110 offset:16
	ds_read_u16 v114, v110 offset:24
	ds_read_u16 v115, v110 offset:32
	ds_read_u16 v116, v110 offset:40
	ds_read_u16 v117, v110 offset:48
	ds_read_u16 v118, v110 offset:56
	s_and_b32 s24, s21, 0x180
	s_lshl_b32 s46, s24, 1
	v_add_u32_e32 v136, s46, v64
	s_waitcnt lgkmcnt(0)
	v_lshl_add_u32 v111, v111, 9, v136
	v_lshl_add_u32 v112, v112, 9, v136
	v_lshl_add_u32 v113, v113, 9, v136
	v_lshl_add_u32 v114, v114, 9, v136
	v_lshl_add_u32 v115, v115, 9, v136
	v_lshl_add_u32 v116, v116, 9, v136
	v_lshl_add_u32 v117, v117, 9, v136
	v_lshl_add_u32 v118, v118, 9, v136
	s_waitcnt vmcnt(7)
	ds_write_b128 v73, v[0:3] offset:8192
	global_load_dwordx4 v[0:3], v111, s[54:55]
	s_waitcnt vmcnt(7)
	ds_write_b128 v74, v[4:7] offset:9216
	global_load_dwordx4 v[4:7], v112, s[54:55]
	s_waitcnt vmcnt(7)
	ds_write_b128 v75, v[8:11] offset:10240
	global_load_dwordx4 v[8:11], v113, s[54:55]
	s_waitcnt vmcnt(7)
	ds_write_b128 v76, v[12:15] offset:11264
	global_load_dwordx4 v[12:15], v114, s[54:55]
	s_waitcnt vmcnt(7)
	ds_write_b128 v73, v[16:19] offset:12288
	global_load_dwordx4 v[16:19], v115, s[54:55]
	s_waitcnt vmcnt(7)
	ds_write_b128 v74, v[20:23] offset:13312
	global_load_dwordx4 v[20:23], v116, s[54:55]
	s_waitcnt vmcnt(7)
	ds_write_b128 v75, v[24:27] offset:14336
	global_load_dwordx4 v[24:27], v117, s[54:55]
	s_waitcnt vmcnt(7)
	ds_write_b128 v76, v[28:31] offset:15360
	global_load_dwordx4 v[28:31], v118, s[54:55]
	s_branch .LBB0_788
.Lpv_first:
	s_and_b32 s24, s22, 0xe0
	v_lshl_add_u32 v240, s24, 1, v72
	ds_read_u16 v241, v240
	ds_read_u16 v242, v240 offset:8
	ds_read_u16 v243, v240 offset:16
	ds_read_u16 v244, v240 offset:24
	ds_read_u16 v245, v240 offset:32
	ds_read_u16 v246, v240 offset:40
	ds_read_u16 v247, v240 offset:48
	ds_read_u16 v248, v240 offset:56
	s_and_b32 s24, s21, 0x180
	s_lshl_b32 s46, s24, 1
	v_add_u32_e32 v136, s46, v64
	s_waitcnt lgkmcnt(0)
	v_lshl_add_u32 v241, v241, 9, v136
	v_lshl_add_u32 v242, v242, 9, v136
	v_lshl_add_u32 v243, v243, 9, v136
	v_lshl_add_u32 v244, v244, 9, v136
	v_lshl_add_u32 v245, v245, 9, v136
	v_lshl_add_u32 v246, v246, 9, v136
	v_lshl_add_u32 v247, v247, 9, v136
	v_lshl_add_u32 v248, v248, 9, v136
	s_waitcnt vmcnt(7)
	ds_write_b128 v73, v[96:99] offset:8192
	global_load_dwordx4 v[0:3], v241, s[54:55]
	s_waitcnt vmcnt(7)
	ds_write_b128 v74, v[100:103] offset:9216
	global_load_dwordx4 v[4:7], v242, s[54:55]
	s_waitcnt vmcnt(7)
	ds_write_b128 v75, v[104:107] offset:10240
	global_load_dwordx4 v[8:11], v243, s[54:55]
	s_waitcnt vmcnt(7)
	ds_write_b128 v76, v[108:111] offset:11264
	global_load_dwordx4 v[12:15], v244, s[54:55]
	s_waitcnt vmcnt(7)
	ds_write_b128 v73, v[112:115] offset:12288
	global_load_dwordx4 v[16:19], v245, s[54:55]
	s_waitcnt vmcnt(7)
	ds_write_b128 v74, v[116:119] offset:13312
	global_load_dwordx4 v[20:23], v246, s[54:55]
	s_waitcnt vmcnt(7)
	ds_write_b128 v75, v[120:123] offset:14336
	global_load_dwordx4 v[24:27], v247, s[54:55]
	s_waitcnt vmcnt(7)
	ds_write_b128 v76, v[124:127] offset:15360
	global_load_dwordx4 v[28:31], v248, s[54:55]
	s_branch .LBB0_788
